# mLSTM chain: prefetch addresses kept as running 64-bit pointers (one add per stream per chunk) instead of recomputed 64-bit multiply-adds
# speedup vs baseline: 1.1077x; 1.0070x over previous
; #define LAS __attribute__((address_space(3)))
; __device__ __forceinline__ void mlstm_task(const Ctx& c, int p, int l, int q, int h, int slab) {
;     bf16_t* Z = (bf16_t*)(wsg(c) + WS_Z); const float* gif = (const float*)(wsg(c) + WS_GIF);
;     const bf16_t* SLp = (const bf16_t*)(wsg(c) + WS_SL) + (size_t)(q < 2 ? q * 512 + h * 128 : 1024 + (q - 2) * 4 + h) * 4096 + (c.tid >> 3) * 64 + 8 * (c.tid & 7);
;     const Seq sq = seq_of(p, q); const int tid = c.tid, lane = c.lane, w = c.wave;
;     LAS bf16_t* Qs = (LAS bf16_t*)(c.lds); LAS bf16_t* Ks = (LAS bf16_t*)(c.lds + 33792); LAS bf16_t* KT = (LAS bf16_t*)(c.lds + 67584); LAS bf16_t* VT = (LAS bf16_t*)(c.lds + 104448);
;     LAS bf16_t* VgT = (LAS bf16_t*)(c.lds + 109200); LAS bf16_t* Cs = (LAS bf16_t*)(c.lds + 113952); LAS bf16_t* St = (LAS bf16_t*)(c.lds + 131376);
;     LAS float* sc = (LAS float*)(c.lds + 140592);
;     LAS float* bcum = sc; LAS float* igs = sc + 64; LAS float* mts = sc + 128; LAS float* wint = sc + 192; LAS float* gsrc = sc + 256; LAS float* dd = sc + 320; LAS float* misc = sc + 384; LAS float* esc = sc + 392;
;     const int nvalid = sq.sample ? DSEQ : 64, nch = sq.sample ? 1 : SEQ / 64;
;     const float bi = inp(c, I_IFB)[l * 8 + h], bf = inp(c, I_IFB)[l * 8 + 4 + h];
;     f32x4 cacc[3][2];
; #pragma unroll
;     for (int vi = 0; vi < 3; ++vi)
; #pragma unroll
;         for (int e = 0; e < 2; ++e)
; #pragma unroll
;             for (int r = 0; r < 4; ++r) {
;                 const int vloc = 16 * vi + (lane >> 4) * 4 + r, d = 16 * (2 * w + e) + (lane & 15); float v0 = 0.f;
;                 if (sq.sample) { if (vloc < 32) v0 = inp(c, I_SMC)[(((size_t)l * DB + sq.b) * 4 + h) * 65536 + (size_t)(slab * 32 + vloc) * 256 + d];
;                                  else if (vloc == 32) v0 = inp(c, I_SMN)[(((size_t)l * DB + sq.b) * 4 + h) * 256 + d]; }
;                 cacc[vi][e][r] = v0;
;             }
;     if (tid < 64) VT[32 * 72 + tid] = (bf16_t)0x3f80u;
;     if (tid == 0) misc[0] = sq.sample ? inp(c, I_SMM)[((size_t)l * DB + sq.b) * 4 + h] : 0.f;
;     unsigned zz = 0u; asm volatile("" : "+v"(zz)); const u32x4 zv = {zz, zz, zz, zz};
;     u32x4 pq[4], pk[4], pvv = zv, psl = zv; float pgi = 0.f, pgf = 0.f; int pfc = 0;
;     ...
;     ML_PREFETCH(sq.row0);
;     __syncthreads();
.LBB0_1582:
	s_or_b64 exec, exec, s[18:19]
	s_mov_b64 s[18:19], 0x1e0f4100
	v_readlane_b32 s36, v254, 42
	v_lshl_add_u64 v[92:93], v[2:3], 0, s[18:19]
	s_add_i32 s28, s84, 0x1bd20
	v_lshl_add_u32 v2, v11, 1, s84
	v_lshrrev_b32_e32 v11, 3, v183
	s_lshl_b32 s34, s36, 6
	v_and_b32_e32 v90, 15, v182
	s_add_i32 s30, s84, 0x10800
	s_add_i32 s31, s84, 0x20130
	v_mul_lo_u32 v11, v11, s81
	s_add_i32 s34, s28, s34
	v_add3_u32 v118, s31, v11, v0
	v_lshl_add_u32 v0, v90, 1, s34
	v_and_b32_e32 v11, 0x7f, v183
	v_mov_b32_e32 v62, s30
	s_movk_i32 s34, 0x120
	v_lshl_add_u32 v61, v11, 2, s84
	v_mad_u32_u24 v11, v11, s34, v62
	s_lshl_b32 s34, s36, 3
	s_lshl_b32 s67, s36, 4
	s_and_b32 s75, s34, -16
	s_and_b32 s71, s67, 16
	s_mul_i32 s34, s75, 0x210
	s_mul_i32 s35, s71, 0x210
	s_add_i32 s61, s84, 0x22730
	s_add_i32 s29, s84, 0x22930
	v_ashrrev_i32_e32 v3, 2, v182
	s_lshl_b32 s74, s36, 5
	s_add_i32 s64, s84, 0x1aa90
	s_add_i32 s65, s84, 0x22830
	s_add_i32 s69, s84, 0x22a30
	s_add_i32 s66, s84, 0x22b50
	s_add_i32 s34, s84, s34
	s_add_i32 s28, s28, s35
	v_and_b32_e32 v115, -4, v3
	v_mul_u32_u24_e32 v63, 0x108, v90
	s_cmp_lt_i32 s36, 4
	v_lshlrev_b32_e32 v88, 2, v6
	v_mov_b32_e32 v89, v31
	v_or_b32_e32 v7, 1, v115
	v_lshlrev_b32_e32 v63, 1, v63
	v_and_b32_e32 v68, -16, v182
	s_cselect_b64 s[82:83], -1, 0
	v_mul_u32_u24_e32 v70, 0x48, v90
	v_lshl_add_u64 v[94:95], s[26:27], 0, v[88:89]
	s_add_i32 s26, s84, 0x1ff20
	v_or_b32_e32 v51, 2, v115
	v_lshlrev_b32_e32 v70, 1, v70
	v_add3_u32 v89, s26, v63, v68
	s_add_i32 s26, s84, 0x1aa00
	s_movk_i32 s87, 0x210
	v_cmp_gt_i32_e64 s[46:47], 33, v7
	v_ashrrev_i32_e32 v7, 4, v183
	v_or_b32_e32 v60, 3, v3
	v_cmp_gt_i32_e32 vcc, 64, v50
	v_add3_u32 v131, s26, v70, v68
	v_mad_u64_u32 v[96:97], s[26:27], v1, s87, v[2:3]
	v_mad_u64_u32 v[98:99], s[26:27], v5, s87, v[2:3]
	v_mad_u64_u32 v[100:101], s[26:27], v8, s87, v[2:3]
	v_mad_u64_u32 v[102:103], s[26:27], v13, s87, v[2:3]
	v_mul_u32_u24_e32 v2, 0x90, v4
	v_lshlrev_b32_e32 v6, 1, v50
	v_cmp_gt_i32_e64 s[48:49], 33, v51
	s_xor_b64 s[62:63], s[12:13], -1
	v_and_b32_e32 v51, -8, v7
	v_add3_u32 v69, s84, v63, v68
	s_add_i32 s93, s84, 0x22b34
	s_add_i32 s97, s84, 0x22b38
	v_writelane_b32 v254, s84, 58
	v_add3_u32 v97, s60, v2, v6
	v_cmp_gt_i32_e64 s[50:51], 33, v60
	v_mul_lo_u32 v6, v60, s87
	s_and_b64 s[84:85], s[62:63], vcc
	v_mul_lo_u32 v60, v51, s87
	v_lshl_add_u32 v99, v51, 1, v11
	v_ashrrev_i32_e32 v51, 4, v9
	s_movk_i32 s62, 0x48
	v_ashrrev_i32_e32 v9, 6, v9
	v_and_b32_e32 v62, 63, v183
	v_mul_lo_u32 v9, v9, s62
	v_add_lshl_u32 v9, v9, v62, 1
	v_add_u32_e32 v133, s60, v9
	v_add_u32_e32 v134, s64, v9
	v_ashrrev_i32_e32 v9, 6, v10
	v_add3_u32 v120, s34, v63, v68
	v_add3_u32 v121, s28, v63, v68
	v_and_b32_e32 v63, -8, v51
	v_mul_lo_u32 v9, v9, s62
	v_lshl_add_u32 v101, v63, 1, v11
	v_ashrrev_i32_e32 v11, 6, v183
	v_add_lshl_u32 v9, v9, v62, 1
	s_mul_i32 s28, s75, 0x90
	s_mul_i32 s34, s71, 0x90
	v_mul_lo_u32 v11, v11, s62
	v_add_u32_e32 v135, s60, v9
	v_add_u32_e32 v144, s64, v9
	v_ashrrev_i32_e32 v9, 6, v49
	s_add_i32 s28, s31, s28
	s_add_i32 s34, s60, s34
	v_add_u32_e32 v71, s75, v115
	v_add_lshl_u32 v11, v11, v62, 1
	v_mul_lo_u32 v9, v9, s62
	v_add3_u32 v122, s28, v70, v68
	v_add3_u32 v123, s34, v70, v68
	v_add3_u32 v72, s31, v70, v68
	v_add3_u32 v124, s64, v70, v68
	v_add3_u32 v125, s30, v70, v68
	v_cmp_gt_i32_e64 s[56:57], 4, v3
	v_cmp_gt_i32_e64 s[58:59], 0, v3
	v_or_b32_e32 v7, 7, v7
	v_mul_lo_u32 v68, v63, s87
	v_or_b32_e32 v51, 7, v51
	v_add_u32_e32 v103, s60, v11
	v_add_u32_e32 v132, s64, v11
	v_add_lshl_u32 v9, v9, v62, 1
	v_or_b32_e32 v11, 2, v71
	v_add_lshl_u32 v63, v115, s67, 2
	v_add_lshl_u32 v3, s67, v3, 2
	v_lshl_add_u32 v119, v62, 2, s29
	v_lshlrev_b32_e32 v73, 2, v182
	s_mul_i32 s81, s36, 0x2100
	s_mul_i32 s86, s36, 0x900
	v_mul_lo_u32 v2, v115, s87
	v_mul_lo_u32 v7, v7, s87
	v_mul_lo_u32 v51, v51, s87
	v_add_u32_e32 v145, s60, v9
	v_add_u32_e32 v146, s64, v9
	v_lshlrev_b32_e32 v9, 2, v71
	v_or_b32_e32 v10, 1, v71
	v_lshlrev_b32_e32 v49, 2, v11
	v_or_b32_e32 v62, 3, v71
	v_add_u32_e32 v151, s65, v63
	v_add_u32_e32 v152, s66, v63
	v_or_b32_e32 v63, 8, v63
	v_add_u32_e32 v155, s61, v3
	v_add_u32_e32 v156, s69, v3
	v_or_b32_e32 v3, 8, v3
; __device__ __forceinline__ void mlstm_task(const Ctx& c, int p, int l, int q, int h, int slab) {
;     ...
;     unsigned zz = 0u; asm volatile("" : "+v"(zz)); const u32x4 zv = {zz, zz, zz, zz};
;     u32x4 pq[4], pk[4], pvv = zv, psl = zv; float pgi = 0.f, pgf = 0.f; int pfc = 0;
;     ...
;     ML_PREFETCH(sq.row0);
;     ...
;         if (ck + 1 < nch) ML_PREFETCH(rbase + 64);
	s_or_b32 s89, s74, 16
	v_add3_u32 v185, v50, s68, 64
	v_add3_u32 v186, v182, s68, 64
	v_add3_u32 v187, v1, s68, 64
	v_add3_u32 v188, v5, s68, 64
	v_add3_u32 v189, v8, s68, 64
	v_add3_u32 v190, v13, s68, 64
	s_add_i32 s68, s68, s75
	s_mov_b32 s80, 1
	v_cmp_gt_i32_e64 s[18:19], 15, v115
	v_cmp_gt_i32_e64 s[20:21], 14, v115
	v_cmp_gt_i32_e64 s[22:23], -1, v115
	v_cmp_gt_i32_e64 s[24:25], -2, v115
	v_add_u32_e32 v126, s61, v73
	v_add_u32_e32 v127, s65, v73
	v_add_u32_e32 v128, s29, v73
	v_lshl_add_u32 v129, v182, 1, s64
	v_add_u32_e32 v130, s66, v73
	s_mov_b32 s96, 0
	v_cmp_eq_u32_e64 s[28:29], 0, v182
	v_cmp_eq_u32_e64 s[30:31], 0, v90
	v_cmp_gt_i32_e64 s[34:35], 1, v182
	v_cmp_gt_i32_e64 s[36:37], 2, v182
	v_cmp_gt_i32_e64 s[38:39], 4, v182
	v_cmp_gt_i32_e64 s[40:41], 8, v182
	v_cmp_gt_i32_e64 s[26:27], 16, v182
	v_cmp_gt_i32_e64 s[42:43], 32, v182
	v_cmp_gt_i32_e64 s[44:45], 33, v115
	v_cmp_gt_i32_e64 s[52:53], 17, v115
	v_cmp_gt_i32_e64 s[54:55], 16, v115
	v_add_u32_e32 v147, s65, v9
	v_add_u32_e32 v148, s66, v9
	v_add_u32_e32 v149, s65, v49
	v_add_u32_e32 v150, s66, v49
	v_add_u32_e32 v153, s65, v63
	v_add_u32_e32 v154, s66, v63
	v_add_u32_e32 v157, s61, v3
	v_add_u32_e32 v158, s69, v3
	v_cmp_gt_i32_e64 s[60:61], 64, v71
	v_add_u32_e32 v159, s69, v9
	v_cmp_gt_i32_e64 s[62:63], 64, v10
	v_lshl_add_u32 v160, v10, 2, s69
	v_cmp_gt_i32_e64 s[64:65], 64, v11
	v_add_u32_e32 v161, s69, v49
	v_cmp_gt_i32_e64 s[66:67], 64, v62
	v_lshl_add_u32 v184, v62, 2, s69
	s_mulk_i32 s89, 0x90
	v_add_u32_e32 v191, s68, v115
	v_lshlrev_b32_e32 v104, 1, v4
	v_add_u32_e32 v192, v61, v60
	v_add_u32_e32 v193, v61, v7
	v_add_u32_e32 v194, v61, v68
	v_add_u32_e32 v195, v61, v51
	v_add_u32_e32 v196, s81, v69
	v_add_u32_e32 v197, s86, v72
	v_add_u32_e32 v198, v0, v2
	v_add_u32_e32 v199, v0, v6
	s_mov_b32 s75, 0
	v_mov_b32_e32 v49, v48
	v_mov_b32_e32 v50, v48
	v_mov_b32_e32 v51, v48
	v_mov_b32_e32 v60, v48
	v_mov_b32_e32 v61, v48
	v_mov_b32_e32 v62, v48
	v_mov_b32_e32 v63, v48
	v_mov_b32_e32 v72, v48
	v_mov_b32_e32 v73, v48
	v_mov_b32_e32 v74, v48
	v_mov_b32_e32 v75, v48
	v_mov_b32_e32 v68, v48
	v_mov_b32_e32 v69, v48
	v_mov_b32_e32 v70, v48
	v_mov_b32_e32 v71, v48
	v_mov_b32_e32 v76, v48
	v_mov_b32_e32 v77, v48
	v_mov_b32_e32 v78, v48
	v_mov_b32_e32 v79, v48
	v_mov_b32_e32 v80, v48
	v_mov_b32_e32 v81, v48
	v_mov_b32_e32 v82, v48
	v_mov_b32_e32 v83, v48
	s_ashr_i32 s81, s80, 31
	s_lshl_b64 s[68:69], s[80:81], 13
	v_lshl_add_u64 v[208:209], v[92:93], 0, s[68:69]
	v_add_u32_e32 v0, s96, v187
	v_mov_b64_e32 v[2:3], s[72:73]
	v_mad_i64_i32 v[2:3], s[86:87], v0, s33, v[2:3]
	s_lshl_b32 s90, s88, 1
	v_lshl_add_u64 v[2:3], v[2:3], 0, s[90:91]
	v_lshl_add_u64 v[2:3], v[2:3], 0, v[30:31]
	v_add_co_u32_e32 v210, vcc, 0x800, v2
	s_nop 1
	v_addc_co_u32_e32 v211, vcc, 0, v3, vcc
	v_add_u32_e32 v0, s96, v188
	v_mov_b64_e32 v[2:3], s[72:73]
	v_mad_i64_i32 v[2:3], s[86:87], v0, s33, v[2:3]
	s_lshl_b32 s90, s88, 1
	v_lshl_add_u64 v[2:3], v[2:3], 0, s[90:91]
	v_lshl_add_u64 v[2:3], v[2:3], 0, v[30:31]
	v_add_co_u32_e32 v212, vcc, 0x800, v2
	s_nop 1
	v_addc_co_u32_e32 v213, vcc, 0, v3, vcc
	v_add_u32_e32 v0, s96, v189
	v_mov_b64_e32 v[2:3], s[72:73]
	v_mad_i64_i32 v[2:3], s[86:87], v0, s33, v[2:3]
	s_lshl_b32 s90, s88, 1
	v_lshl_add_u64 v[2:3], v[2:3], 0, s[90:91]
	v_lshl_add_u64 v[2:3], v[2:3], 0, v[30:31]
	v_add_co_u32_e32 v214, vcc, 0x800, v2
	s_nop 1
	v_addc_co_u32_e32 v215, vcc, 0, v3, vcc
	v_add_u32_e32 v0, s96, v190
	v_mov_b64_e32 v[2:3], s[72:73]
	v_mad_i64_i32 v[2:3], s[86:87], v0, s33, v[2:3]
	s_lshl_b32 s90, s88, 1
	v_lshl_add_u64 v[2:3], v[2:3], 0, s[90:91]
	v_lshl_add_u64 v[2:3], v[2:3], 0, v[30:31]
	v_add_co_u32_e32 v216, vcc, 0x800, v2
	s_nop 1
	v_addc_co_u32_e32 v217, vcc, 0, v3, vcc
	v_add_u32_e32 v2, s96, v185
	v_mov_b64_e32 v[0:1], s[72:73]
	v_mad_i64_i32 v[0:1], s[86:87], v2, s33, v[0:1]
	s_lshl_b32 s90, s88, 1
	v_lshl_add_u64 v[0:1], v[0:1], 0, s[90:91]
	s_lshl_b32 s90, s92, 1
	v_lshl_add_u64 v[0:1], v[0:1], 0, s[90:91]
	v_mov_b32_e32 v105, v31
	v_lshl_add_u64 v[0:1], v[0:1], 0, v[104:105]
	v_add_co_u32_e32 v218, vcc, 0x1000, v0
	s_nop 1
	v_addc_co_u32_e32 v219, vcc, 0, v1, vcc
	s_waitcnt vmcnt(0) lgkmcnt(0)
	s_barrier
	s_branch .LBB0_1584

; #define LAS __attribute__((address_space(3)))
; __device__ __forceinline__ void mlstm_task(const Ctx& c, int p, int l, int q, int h, int slab) {
;     ...
;     ML_PREFETCH(sq.row0);
;     __syncthreads();
;     for (int ck = 0; ck < nch; ++ck) {
;         const int rbase = sq.row0 + ck * 64;
; #pragma unroll
;         for (int i = 0; i < 4; ++i) {
;             const int piece = tid + 512 * i, t = piece >> 5, pc = piece & 31;
;             *(LAS u32x4*)(Qs + t * 264 + 8 * pc) = pq[i]; *(LAS u32x4*)(Ks + t * 264 + 8 * pc) = pk[i];
;         }
;         *(LAS u32x4*)(St + (tid >> 3) * 72 + 8 * (tid & 7)) = psl;
.Lml_top_a:
	s_or_b64 exec, exec, s[68:69]
	ds_write_b128 v96, v[14:17]
	ds_write_b128 v96, v[40:43] offset:33792
	ds_write_b128 v98, v[18:21]
	ds_write_b128 v98, v[44:47] offset:33792
	ds_write_b128 v100, v[22:25]
	ds_write_b128 v100, v[52:55] offset:33792
	ds_write_b128 v102, v[26:29]
	ds_write_b128 v102, v[64:67] offset:33792
	ds_write_b128 v118, v[36:39]
	s_cmpk_gt_u32 s75, 0x7e
	s_cbranch_scc1 .Lml_top_b
	global_load_dwordx4 v[36:39], v[208:209], off
	global_load_dwordx4 v[14:17], v[210:211], off
	global_load_dwordx4 v[40:43], v[210:211], off offset:2048
	global_load_dwordx4 v[18:21], v[212:213], off
	global_load_dwordx4 v[44:47], v[212:213], off offset:2048
	global_load_dwordx4 v[22:25], v[214:215], off
	global_load_dwordx4 v[52:55], v[214:215], off offset:2048
	global_load_dwordx4 v[26:29], v[216:217], off
	global_load_dwordx4 v[64:67], v[216:217], off offset:2048
	v_cndmask_b32_e64 v59, v12, v59, s[12:13]
	v_cndmask_b32_e64 v58, v12, v58, s[12:13]
	v_cndmask_b32_e64 v57, v12, v57, s[12:13]
	v_cndmask_b32_e64 v56, v12, v56, s[12:13]
	s_and_saveexec_b64 s[68:69], s[84:85]
	global_load_dwordx4 v[56:59], v[218:219], off offset:2048
	s_or_b64 exec, exec, s[68:69]
	s_movk_i32 s90, 0x2000
	v_lshl_add_u64 v[208:209], v[208:209], 0, s[90:91]
	s_mov_b32 s90, 0x108000
	v_lshl_add_u64 v[210:211], v[210:211], 0, s[90:91]
	v_lshl_add_u64 v[212:213], v[212:213], 0, s[90:91]
	v_lshl_add_u64 v[214:215], v[214:215], 0, s[90:91]
	v_lshl_add_u64 v[216:217], v[216:217], 0, s[90:91]
	v_lshl_add_u64 v[218:219], v[218:219], 0, s[90:91]
